# v69: v68 + cross-XCD stage of the group-wide seams in one step: each XCD's lq0 workgroup adds 1 to TOP (non-returning) and polls TOP until 4*round, no TOPGEN hop
# baseline (speedup 1.0000x reference)
.Lhb_ltop_g1:
	s_mov_b64 exec, 1
	buffer_wbl2 sc1
	v_readlane_b32 vcc_lo, v255, 55
	v_readlane_b32 vcc_hi, v254, 7
	s_nop 1
	s_add_i32 vcc_lo, vcc_lo, 1
	v_mov_b32_e32 v2, vcc_hi
	v_writelane_b32 v255, vcc_lo, 55
	v_mov_b32_e32 v0, vcc_lo
	v_readlane_b32 vcc_hi, v254, 8
	v_mov_b32_e32 v5, 1
	s_nop 1
	v_mov_b32_e32 v3, vcc_hi
	s_waitcnt vmcnt(0)
	global_atomic_add v[2:3], v5, off
	v_lshlrev_b32_e32 v0, 2, v0
	v_mov_b32_e32 v4, 0
